# barriers around the up GEMM become 8-workgroup group barriers (blockIdx%32 classes exchange A2/ssq/U only among themselves); same release/acquire fences
# baseline (speedup 1.0000x reference)
; __device__ __forceinline__ unsigned xb_ld(unsigned* p)              { return __hip_atomic_load(p, __ATOMIC_RELAXED, __HIP_MEMORY_SCOPE_AGENT); }
; __device__ __forceinline__ unsigned xb_add(unsigned* p, unsigned v) { return __hip_atomic_fetch_add(p, v, __ATOMIC_RELAXED, __HIP_MEMORY_SCOPE_AGENT); }
; #define XB_SPIN(cond, bar) do { unsigned _sp = 0; while (cond) { __builtin_amdgcn_s_sleep(1); \
;     if ((++_sp & 255u) == 0u) { if (xb_ld(&(bar)[XB_TMO])) break; if (_sp > XB_SPIN_CAP) { atomicAdd(&(bar)[XB_TMO], 1u); break; } } } } while (0)
; __device__ __forceinline__ void xcd_barrier(const XcdBarrier& b) {
;     asm volatile("s_waitcnt vmcnt(0)" ::: "memory");
;     __syncthreads();
;     if (threadIdx.x == 0) {
;         unsigned* bar = b.bar;
;         __builtin_amdgcn_s_waitcnt(0);
;         unsigned nloc = b.st[0], nx = b.st[1];
;         if (nloc == 0u) { xcd_barrier_complete(bar, b.x, nloc, nx); b.st[0] = nloc; b.st[1] = nx; }
;         const unsigned old = xb_add(&bar[XB_XSUB(b.x)], 1u);
;         const unsigned gen = old / nloc;
;         if (old + 1u == (gen + 1u) * nloc) {
;             __builtin_amdgcn_fence(__ATOMIC_RELEASE, "agent");
;             asm volatile("s_waitcnt vmcnt(0)" ::: "memory");
;             const unsigned og = xb_add(&bar[XB_TOP], 1u);
;             const unsigned tg = og / nx;
;             if (og + 1u == (tg + 1u) * nx) xb_add(&bar[XB_TOPGEN], 1u);
;             else XB_SPIN(xb_ld(&bar[XB_TOPGEN]) == tg, bar);
;             __builtin_amdgcn_fence(__ATOMIC_ACQUIRE, "agent");
;             xb_add(&bar[XB_XGEN(b.x)], 1u);
;             asm volatile("s_waitcnt vmcnt(0)" ::: "memory");
;         } else {
;             XB_SPIN(xb_ld(&bar[XB_XGEN(b.x)]) == gen, bar);
;             __builtin_amdgcn_fence(__ATOMIC_ACQUIRE, "agent");
;             asm volatile("s_waitcnt vmcnt(0)" ::: "memory");
;         }
;     }
;     __syncthreads();
; }
.LBB0_823:
	s_cmp_lt_i32 s19, 7
	s_cbranch_scc1 .LBB0_877
	s_waitcnt vmcnt(0)
	s_waitcnt vmcnt(0) lgkmcnt(0)
	s_barrier
	s_mov_b64 s[0:1], exec
	v_readlane_b32 s2, v247, 37
	v_readlane_b32 s3, v247, 38
	s_and_b64 s[2:3], s[0:1], s[2:3]
	s_mov_b64 exec, s[2:3]
	s_cbranch_execz .LBB0_876
	buffer_wbl2 sc1
	s_and_b32 s2, s90, 31
	s_lshl_b32 s2, s2, 6
	s_add_u32 s2, s62, s2
	s_addc_u32 s3, s63, 0
	s_add_u32 s2, s2, 0x8000
	s_addc_u32 s3, s3, 0
	v_mov_b32_e32 v1, 0
	v_mov_b32_e32 v2, 1
	s_mov_b32 s4, 0
	s_waitcnt vmcnt(0) lgkmcnt(0)
	global_atomic_add v1, v2, s[2:3]
.Lgrpbar1_spin:
	global_load_dword v3, v1, s[2:3] sc1
	s_waitcnt vmcnt(0)
	v_cmp_lt_u32_e32 vcc, 7, v3
	s_cbranch_vccnz .Lgrpbar1_done
	s_sleep 1
	s_add_i32 s4, s4, 1
	s_cmp_lt_u32 s4, 0x200000
	s_cbranch_scc1 .Lgrpbar1_spin
.Lgrpbar1_done:
	buffer_inv sc1
	s_waitcnt vmcnt(0)

; __device__ __forceinline__ unsigned xb_ld(unsigned* p)              { return __hip_atomic_load(p, __ATOMIC_RELAXED, __HIP_MEMORY_SCOPE_AGENT); }
; __device__ __forceinline__ unsigned xb_add(unsigned* p, unsigned v) { return __hip_atomic_fetch_add(p, v, __ATOMIC_RELAXED, __HIP_MEMORY_SCOPE_AGENT); }
; #define XB_SPIN(cond, bar) do { unsigned _sp = 0; while (cond) { __builtin_amdgcn_s_sleep(1); \
;     if ((++_sp & 255u) == 0u) { if (xb_ld(&(bar)[XB_TMO])) break; if (_sp > XB_SPIN_CAP) { atomicAdd(&(bar)[XB_TMO], 1u); break; } } } } while (0)
; __device__ __forceinline__ void xcd_barrier(const XcdBarrier& b) {
;     asm volatile("s_waitcnt vmcnt(0)" ::: "memory");
;     __syncthreads();
;     if (threadIdx.x == 0) {
;         unsigned* bar = b.bar;
;         __builtin_amdgcn_s_waitcnt(0);
;         unsigned nloc = b.st[0], nx = b.st[1];
;         if (nloc == 0u) { xcd_barrier_complete(bar, b.x, nloc, nx); b.st[0] = nloc; b.st[1] = nx; }
;         const unsigned old = xb_add(&bar[XB_XSUB(b.x)], 1u);
;         const unsigned gen = old / nloc;
;         if (old + 1u == (gen + 1u) * nloc) {
;             __builtin_amdgcn_fence(__ATOMIC_RELEASE, "agent");
;             asm volatile("s_waitcnt vmcnt(0)" ::: "memory");
;             const unsigned og = xb_add(&bar[XB_TOP], 1u);
;             const unsigned tg = og / nx;
;             if (og + 1u == (tg + 1u) * nx) xb_add(&bar[XB_TOPGEN], 1u);
;             else XB_SPIN(xb_ld(&bar[XB_TOPGEN]) == tg, bar);
;             __builtin_amdgcn_fence(__ATOMIC_ACQUIRE, "agent");
;             xb_add(&bar[XB_XGEN(b.x)], 1u);
;             asm volatile("s_waitcnt vmcnt(0)" ::: "memory");
;         } else {
;             XB_SPIN(xb_ld(&bar[XB_XGEN(b.x)]) == gen, bar);
;             __builtin_amdgcn_fence(__ATOMIC_ACQUIRE, "agent");
;             asm volatile("s_waitcnt vmcnt(0)" ::: "memory");
;         }
;     }
;     __syncthreads();
; }
.LBB0_902:
	s_cmp_lt_i32 s19, 9
	s_cbranch_scc1 .LBB0_956
	s_waitcnt vmcnt(0)
	s_waitcnt vmcnt(0) lgkmcnt(0)
	s_barrier
	s_mov_b64 s[0:1], exec
	v_readlane_b32 s2, v247, 37
	v_readlane_b32 s3, v247, 38
	s_and_b64 s[2:3], s[0:1], s[2:3]
	s_mov_b64 exec, s[2:3]
	s_cbranch_execz .LBB0_955
	buffer_wbl2 sc1
	s_and_b32 s2, s90, 31
	s_lshl_b32 s2, s2, 6
	s_add_u32 s2, s62, s2
	s_addc_u32 s3, s63, 0
	s_add_u32 s2, s2, 0x9000
	s_addc_u32 s3, s3, 0
	v_mov_b32_e32 v1, 0
	v_mov_b32_e32 v2, 1
	s_mov_b32 s4, 0
	s_waitcnt vmcnt(0) lgkmcnt(0)
	global_atomic_add v1, v2, s[2:3]
